# FFN fix-up rows: 14 loads per iteration issued together with one wait instead of six load/wait groups
# speedup vs baseline: 1.0279x; 1.0104x over previous
; __device__ __forceinline__ unsigned cvt_pk_bf16(float lo, float hi) { unsigned r; asm volatile("v_cvt_pk_bf16_f32 %0, %1, %2" : "=v"(r) : "v"(lo), "v"(hi)); return r; }
; __device__ __forceinline__ float sigm(float x) { return __builtin_amdgcn_rcpf(1.0f + __expf(-x)); }
; __device__ __forceinline__ void ffnfix_panel(PCP p, int i, int pm, int tid) {
;     ...
;     for (int idx = tid; idx < 2 * 704; idx += 512) {
;         const int r = idx / 704, c = (idx - r * 704) * 4;
;         const float* h0 = head + ((size_t)pm * 2) * NUP; const float* t0 = tail + ((size_t)(pm - 1) * 2) * NUP;
;         const float* r0 = (r == 1) ? h0 + NUP : h0;
;         const float* r1 = (r == 1) ? h0 : t0 + NUP;
;         const float* r2 = (r == 1) ? t0 + NUP : t0;
;         const f32x4 g = *(const f32x4*)(cb + c) + *(const f32x4*)(cw + c) * *(const f32x4*)(r2 + c) + *(const f32x4*)(cw + NUP + c) * *(const f32x4*)(r1 + c) + *(const f32x4*)(cw + 2 * NUP + c) * *(const f32x4*)(r0 + c);
;         const f32x4 v = *(const f32x4*)(cb + DFF + c) + *(const f32x4*)(cw + DFF + c) * *(const f32x4*)(r2 + DFF + c) + *(const f32x4*)(cw + NUP + DFF + c) * *(const f32x4*)(r1 + DFF + c) + *(const f32x4*)(cw + 2 * NUP + DFF + c) * *(const f32x4*)(r0 + DFF + c);
;         u32x2 w; w.x = cvt_pk_bf16(g[0] * sigm(g[0]) * v[0], g[1] * sigm(g[1]) * v[1]); w.y = cvt_pk_bf16(g[2] * sigm(g[2]) * v[2], g[3] * sigm(g[3]) * v[3]);
;         *(u32x2*)(act + ((size_t)pm * 256 + r) * DFF + c) = w;
;     }
.LBB0_1122:
	s_mov_b32 s49, 0x2e8ba2e9
	v_mul_hi_i32 v0, v5, s49
	v_lshrrev_b32_e32 v1, 31, v0
	v_ashrrev_i32_e32 v0, 7, v0
	v_add_u32_e32 v2, v0, v1
	v_add_u32_e32 v1, 0xfffffd40, v5
	s_movk_i32 s49, 0x2c0
	v_cmp_gt_u32_e32 vcc, s49, v1
	v_mov_b32_e32 v1, s48
	v_mov_b32_e32 v3, s43
	v_cndmask_b32_e32 v21, v1, v3, vcc
	v_mov_b32_e32 v3, s47
	v_mov_b32_e32 v6, s42
	v_mul_i32_i24_e32 v0, 0xfffffd40, v2
	v_cndmask_b32_e32 v20, v3, v6, vcc
	v_mov_b32_e32 v6, s37
	v_add_lshl_u32 v0, v0, v5, 2
	v_cndmask_b32_e32 v15, v6, v1, vcc
	v_mov_b32_e32 v1, s29
	v_cndmask_b32_e32 v14, v1, v3, vcc
	v_ashrrev_i32_e32 v1, 31, v0
	v_lshlrev_b64 v[22:23], 2, v[0:1]
	v_lshl_add_u64 v[6:7], s[2:3], 0, v[22:23]
	v_lshl_add_u64 v[10:11], s[0:1], 0, v[22:23]
	v_lshl_add_u64 v[24:25], v[14:15], 0, v[22:23]
	v_lshl_add_u64 v[20:21], v[20:21], 0, v[22:23]
	v_cndmask_b32_e32 v160, 0, v213, vcc
	v_lshl_add_u64 v[18:19], s[42:43], 0, v[160:161]
	v_lshl_add_u64 v[18:19], v[18:19], 0, v[22:23]
	global_load_dwordx4 v[84:87], v[6:7], off
	global_load_dwordx4 v[88:91], v[10:11], off
	global_load_dwordx4 v[92:95], v[24:25], off
	v_lshl_add_u64 v[6:7], s[4:5], 0, v[22:23]
	global_load_dwordx4 v[96:99], v[6:7], off
	global_load_dwordx4 v[100:103], v[20:21], off
	v_lshl_add_u64 v[6:7], s[6:7], 0, v[22:23]
	global_load_dwordx4 v[104:107], v[6:7], off
	global_load_dwordx4 v[108:111], v[18:19], off
	v_lshl_add_u64 v[6:7], s[8:9], 0, v[22:23]
	global_load_dwordx4 v[112:115], v[6:7], off
	v_lshl_add_u64 v[6:7], s[10:11], 0, v[22:23]
	global_load_dwordx4 v[116:119], v[6:7], off
	v_add_co_u32_e32 v14, vcc, s33, v24
	s_nop 1
	v_addc_co_u32_e32 v15, vcc, 0, v25, vcc
	global_load_dwordx4 v[120:123], v[14:15], off offset:3072
	v_lshl_add_u64 v[6:7], s[12:13], 0, v[22:23]
	global_load_dwordx4 v[124:127], v[6:7], off
	v_add_co_u32_e32 v10, vcc, s33, v20
	s_nop 1
	v_addc_co_u32_e32 v11, vcc, 0, v21, vcc
	global_load_dwordx4 v[128:131], v[10:11], off offset:3072
	v_lshl_add_u64 v[6:7], s[14:15], 0, v[22:23]
	global_load_dwordx4 v[132:135], v[6:7], off
	v_add_co_u32_e32 v10, vcc, s33, v18
	s_nop 1
	v_addc_co_u32_e32 v11, vcc, 0, v19, vcc
	global_load_dwordx4 v[136:139], v[10:11], off offset:3072
	s_movk_i32 s49, 0x37f
	v_cmp_lt_i32_e32 vcc, s49, v5
	v_add_u32_e32 v5, 0x200, v5
	s_or_b64 s[82:83], vcc, s[82:83]
	s_waitcnt vmcnt(0)
	v_pk_fma_f32 v[14:15], v[88:89], v[92:93], v[84:85]
	v_pk_fma_f32 v[16:17], v[90:91], v[94:95], v[86:87]
	s_nop 0
	v_pk_fma_f32 v[14:15], v[96:97], v[100:101], v[14:15]
	v_pk_fma_f32 v[16:17], v[98:99], v[102:103], v[16:17]
	s_nop 0
	v_pk_fma_f32 v[28:29], v[104:105], v[108:109], v[14:15]
	v_pk_fma_f32 v[26:27], v[106:107], v[110:111], v[16:17]
	v_pk_fma_f32 v[14:15], v[116:117], v[120:121], v[112:113]
	v_pk_fma_f32 v[16:17], v[118:119], v[122:123], v[114:115]
	s_nop 0
	v_pk_fma_f32 v[14:15], v[124:125], v[128:129], v[14:15]
	v_pk_fma_f32 v[16:17], v[126:127], v[130:131], v[16:17]
	s_nop 0
	v_pk_fma_f32 v[6:7], v[132:133], v[136:137], v[14:15]
	v_pk_fma_f32 v[8:9], v[134:135], v[138:139], v[16:17]
	v_mul_f32_e32 v3, 0xbfb8aa3b, v28
	v_exp_f32_e32 v3, v3
	s_nop 0
	v_add_f32_e32 v3, 1.0, v3
	v_rcp_f32_e32 v3, v3
	s_nop 0
	v_mul_f32_e32 v3, v28, v3
	v_mul_f32_e32 v3, v3, v6
	v_mul_f32_e32 v6, 0xbfb8aa3b, v29
	v_exp_f32_e32 v6, v6
	s_nop 0
	v_add_f32_e32 v6, 1.0, v6
	v_rcp_f32_e32 v6, v6
	s_nop 0
	v_mul_f32_e32 v6, v29, v6
	v_mul_f32_e32 v6, v6, v7
	v_cvt_pk_bf16_f32 v6, v3, v6
	v_mul_f32_e32 v3, 0xbfb8aa3b, v26
	v_mul_f32_e32 v7, 0xbfb8aa3b, v27
	v_exp_f32_e32 v3, v3
	v_exp_f32_e32 v7, v7
	v_add_f32_e32 v3, 1.0, v3
	v_add_f32_e32 v7, 1.0, v7
	v_rcp_f32_e32 v3, v3
	v_rcp_f32_e32 v7, v7
	v_mul_f32_e32 v3, v26, v3
	v_mul_f32_e32 v7, v27, v7
	v_mul_f32_e32 v3, v3, v8
	v_mul_f32_e32 v7, v7, v9
	v_cvt_pk_bf16_f32 v7, v3, v7
	v_ashrrev_i32_e32 v3, 31, v2
	v_lshl_add_u64 v[2:3], s[80:81], 0, v[2:3]
	v_mov_b64_e32 v[8:9], s[24:25]
	v_mad_u64_u32 v[8:9], s[50:51], v2, s46, v[8:9]
	v_mad_i32_i24 v9, v3, s46, v9
	v_lshl_add_u64 v[0:1], v[0:1], 1, v[8:9]
	global_store_dwordx2 v[0:1], v[6:7], off
	s_andn2_b64 exec, exec, s[82:83]
	s_cbranch_execnz .LBB0_1122
	s_branch .LBB0_1111
